# v36 + P7 (y_a conv3 pass): dummy loads touch the rows of the item two steps ahead; item wait vmcnt(4)
# speedup vs baseline: 1.0004x; 1.0004x over previous
.Lya_ld:
	s_add_u32 s50, s46, 0x400000
	s_addc_u32 s51, s47, 0
	s_add_u32 s52, s48, 0x400000
	s_addc_u32 s53, s49, 0
	global_load_dword v100, v3, s[50:51]
	global_load_dword v100, v3, s[50:51] offset:-2048
	global_load_dword v100, v3, s[50:51] offset:-4096
	global_load_dword v100, v3, s[52:53]
	s_waitcnt vmcnt(4)
	s_cmp_eq_u32 s40, 0
	s_cbranch_scc0 .Lya_u1n
	v_lshlrev_b32_e32 v56, 16, v40
	v_and_b32_e32 v57, 0xffff0000, v40
	v_lshlrev_b32_e32 v58, 16, v41
	v_and_b32_e32 v59, 0xffff0000, v41
	v_lshlrev_b32_e32 v60, 16, v42
	v_and_b32_e32 v61, 0xffff0000, v42
	v_lshlrev_b32_e32 v62, 16, v43
	v_and_b32_e32 v63, 0xffff0000, v43
	s_branch .Lya_u0
